# DeltaNet chunk: C2 rhs gather issues all 20 u16 LDS reads before the first wait (3 reused-register stalls removed); step-B epilogue: 16 s_cbranch_execz around 4-5 instruction exec-masked blocks remove
# baseline (speedup 1.0000x reference)
.LBB0_649:
	s_and_b32 s0, s60, 1
	s_add_i32 s64, 16, 0x1c800
	v_mov_b32_e32 v71, v120
	v_mov_b32_e32 v0, v107
	v_mov_b32_e32 v1, v121
	s_cmp_eq_u32 s0, 0
	s_cselect_b64 s[14:15], -1, 0
	v_add_u32_e32 v0, s33, v71
	v_lshlrev_b32_e32 v60, 4, v1
	s_and_b64 s[0:1], s[14:15], exec
	v_mul_lo_u32 v3, v0, s21
	v_add_u32_e32 v0, 16, v60
	s_cselect_b32 s66, 16, s54
	v_add_u32_e32 v69, v0, v3
	v_add_u32_e32 v80, s35, v71
	v_add3_u32 v70, s66, v3, v60
	v_mad_u64_u32 v[86:87], s[0:1], v80, s21, v[0:1]
	ds_read_b128 v[60:63], v69 offset:17408
	ds_read_b128 v[64:67], v70
	ds_read_b128 v[72:75], v86 offset:17408
	ds_read_b128 v[168:171], v69 offset:17472
	ds_read_b128 v[172:175], v70 offset:64
	ds_read_b128 v[176:179], v86 offset:17472
	ds_read_b128 v[180:183], v69 offset:17536
	ds_read_b128 v[184:187], v70 offset:128
	ds_read_b128 v[188:191], v86 offset:17536
	ds_read_b128 v[192:195], v69 offset:17600
	ds_read_b128 v[196:199], v70 offset:192
	ds_read_b128 v[200:203], v86 offset:17600
	s_cselect_b32 s65, s64, s55
	v_lshl_add_u32 v68, v1, 2, s33
	v_lshl_add_u32 v1, v80, 2, s65
	ds_read_b32 v81, v1
	v_lshl_add_u32 v1, v68, 2, s65
	ds_read_b128 v[160:163], v1
	ds_read_b128 v[164:167], v1 offset:256
	v_cmp_ge_i32_e64 s[12:13], v68, v80
	s_waitcnt lgkmcnt(12)
	v_mfma_f32_16x16x32_bf16 v[60:63], v[60:63], v[72:75], 0
	v_mfma_f32_16x16x32_bf16 v[64:67], v[64:67], v[72:75], 0
	s_waitcnt lgkmcnt(9)
	v_mfma_f32_16x16x32_bf16 v[60:63], v[168:171], v[176:179], v[60:63]
	v_mfma_f32_16x16x32_bf16 v[64:67], v[172:175], v[176:179], v[64:67]
	s_waitcnt lgkmcnt(6)
	v_mfma_f32_16x16x32_bf16 v[60:63], v[180:183], v[188:191], v[60:63]
	v_mfma_f32_16x16x32_bf16 v[72:75], v[184:187], v[188:191], v[64:67]
	s_waitcnt lgkmcnt(3)
	v_mfma_f32_16x16x32_bf16 v[64:67], v[192:195], v[200:203], v[60:63]
	v_mfma_f32_16x16x32_bf16 v[60:63], v[196:199], v[200:203], v[72:75]
	s_nop 4
	v_mov_b32_e32 v72, 0
	v_mov_b32_e32 v73, 0
	s_waitcnt lgkmcnt(0)
	s_and_saveexec_b64 s[0:1], s[12:13]
	v_mov_b32_e32 v3, v160
	s_nop 0
	v_sub_f32_e32 v3, v3, v81
	v_mul_f32_e32 v3, 0x3fb8aa3b, v3
	v_exp_f32_e32 v73, v3
.LBB0_651:
	s_or_b64 exec, exec, s[0:1]
	s_and_b64 s[0:1], s[14:15], exec
	s_mov_b32 s0, 0x25900
	s_cselect_b32 s0, 0x1c900, s0
	s_add_i32 s0, s0, 16
	v_cmp_gt_i32_e32 vcc, v68, v80
	v_lshl_add_u32 v3, v68, 2, s0
	s_and_saveexec_b64 s[0:1], vcc
	v_mov_b32_e32 v72, v164
	s_nop 0
	v_mul_f32_e32 v64, v64, v72
	v_mul_f32_e32 v72, v73, v64

.LBB0_655:
	v_mul_f32_e32 v60, v60, v73
	v_cvt_pk_bf16_f32 v60, v60, s0
	v_add_u32_e32 v72, 0x19200, v75
	v_or_b32_e32 v76, 1, v68
	ds_write_b16 v72, v60
	v_cmp_ge_i32_e32 vcc, v76, v80
	v_mov_b32_e32 v72, 0
	v_mov_b32_e32 v60, 0
	s_and_saveexec_b64 s[18:19], vcc
	v_mov_b32_e32 v60, v161
	s_nop 0
	v_sub_f32_e32 v60, v60, v81
	v_mul_f32_e32 v60, 0x3fb8aa3b, v60
	v_exp_f32_e32 v60, v60
.LBB0_657:
	s_or_b64 exec, exec, s[18:19]
	s_and_saveexec_b64 s[18:19], s[12:13]
	v_mov_b32_e32 v72, v165
	s_nop 0
	v_mul_f32_e32 v65, v65, v72
	v_mul_f32_e32 v72, v60, v65

.LBB0_661:
	v_mul_f32_e32 v60, v61, v60
	v_cvt_pk_bf16_f32 v60, v60, s0
	v_add_u32_e32 v61, 0x19200, v65
	v_or_b32_e32 v72, 2, v68
	ds_write_b16 v61, v60
	v_cmp_ge_i32_e32 vcc, v72, v80
	v_mov_b32_e32 v61, 0
	v_mov_b32_e32 v60, 0
	s_and_saveexec_b64 s[12:13], vcc
	v_mov_b32_e32 v60, v162
	s_nop 0
	v_sub_f32_e32 v60, v60, v81
	v_mul_f32_e32 v60, 0x3fb8aa3b, v60
	v_exp_f32_e32 v60, v60
.LBB0_663:
	s_or_b64 exec, exec, s[12:13]
	v_cmp_gt_i32_e32 vcc, v72, v80
	s_and_saveexec_b64 s[12:13], vcc
	v_mov_b32_e32 v61, v166
	s_nop 0
	v_mul_f32_e32 v61, v66, v61
	v_mul_f32_e32 v61, v60, v61

.LBB0_667:
	v_mul_f32_e32 v60, v62, v60
	v_cvt_pk_bf16_f32 v60, v60, s0
	v_add_u32_e32 v61, 0x19200, v65
	v_or_b32_e32 v73, 3, v68
	ds_write_b16 v61, v60
	v_cmp_ge_i32_e32 vcc, v73, v80
	v_mov_b32_e32 v60, 0
	v_mov_b32_e32 v61, 0
	s_and_saveexec_b64 s[0:1], vcc
	v_mov_b32_e32 v61, v163
	s_nop 0
	v_sub_f32_e32 v61, v61, v81
	v_mul_f32_e32 v61, 0x3fb8aa3b, v61
	v_exp_f32_e32 v61, v61
.LBB0_669:
	s_or_b64 exec, exec, s[0:1]
	v_cmp_gt_i32_e32 vcc, v73, v80
	s_and_saveexec_b64 s[0:1], vcc
	v_mov_b32_e32 v60, v167
	s_nop 0
	v_mul_f32_e32 v60, v67, v60
	v_mul_f32_e32 v60, v61, v60

.LBB0_677:
	ds_read_b128 v[160:163], v1
	ds_read_b128 v[164:167], v1 offset:256
	v_add_u32_e32 v71, s63, v71
	v_mad_u64_u32 v[96:97], s[0:1], v71, s21, v[0:1]
	ds_read_b128 v[60:63], v69 offset:17408
	ds_read_b128 v[64:67], v70
	ds_read_b128 v[84:87], v96 offset:17408
	ds_read_b128 v[168:171], v69 offset:17472
	ds_read_b128 v[172:175], v70 offset:64
	ds_read_b128 v[176:179], v96 offset:17472
	ds_read_b128 v[180:183], v69 offset:17536
	ds_read_b128 v[184:187], v70 offset:128
	ds_read_b128 v[188:191], v96 offset:17536
	ds_read_b128 v[192:195], v69 offset:17600
	ds_read_b128 v[196:199], v70 offset:192
	ds_read_b128 v[200:203], v96 offset:17600
	v_lshl_add_u32 v0, v71, 2, s65
	v_cmp_ge_i32_e64 s[12:13], v68, v71
	ds_read_b32 v0, v0
	s_waitcnt lgkmcnt(10)
	v_mfma_f32_16x16x32_bf16 v[60:63], v[60:63], v[84:87], 0
	v_mfma_f32_16x16x32_bf16 v[64:67], v[64:67], v[84:87], 0
	s_waitcnt lgkmcnt(7)
	v_mfma_f32_16x16x32_bf16 v[60:63], v[168:171], v[176:179], v[60:63]
	v_mfma_f32_16x16x32_bf16 v[64:67], v[172:175], v[176:179], v[64:67]
	s_waitcnt lgkmcnt(4)
	v_mfma_f32_16x16x32_bf16 v[60:63], v[180:183], v[188:191], v[60:63]
	v_mfma_f32_16x16x32_bf16 v[84:87], v[184:187], v[188:191], v[64:67]
	v_mov_b32_e32 v70, 0
	s_waitcnt lgkmcnt(1)
	v_mfma_f32_16x16x32_bf16 v[64:67], v[192:195], v[200:203], v[60:63]
	v_mov_b32_e32 v69, 0
	v_mfma_f32_16x16x32_bf16 v[60:63], v[196:199], v[200:203], v[84:87]
	s_waitcnt lgkmcnt(0)
	s_and_saveexec_b64 s[0:1], s[12:13]
	v_mov_b32_e32 v69, v160
	s_nop 0
	v_sub_f32_e32 v69, v69, v0
	v_mul_f32_e32 v69, 0x3fb8aa3b, v69
	v_exp_f32_e32 v69, v69
.LBB0_679:
	s_or_b64 exec, exec, s[0:1]
	v_cmp_gt_i32_e32 vcc, v68, v71
	s_and_saveexec_b64 s[0:1], vcc
	v_mov_b32_e32 v68, v164
	s_nop 0
	v_mul_f32_e32 v64, v64, v68
	v_mul_f32_e32 v70, v69, v64

.LBB0_683:
	v_mul_f32_e32 v60, v60, v69
	v_cvt_pk_bf16_f32 v60, v60, s0
	v_add_u32_e32 v64, 0x19200, v64
	ds_write_b16 v64, v60
	v_cmp_ge_i32_e32 vcc, v76, v71
	v_mov_b32_e32 v64, 0
	v_mov_b32_e32 v60, 0
	s_and_saveexec_b64 s[18:19], vcc
	v_mov_b32_e32 v60, v161
	s_nop 0
	v_sub_f32_e32 v60, v60, v0
	v_mul_f32_e32 v60, 0x3fb8aa3b, v60
	v_exp_f32_e32 v60, v60
.LBB0_685:
	s_or_b64 exec, exec, s[18:19]
	s_and_saveexec_b64 s[18:19], s[12:13]
	v_mov_b32_e32 v64, v165
	s_nop 0
	v_mul_f32_e32 v64, v65, v64
	v_mul_f32_e32 v64, v60, v64

.LBB0_689:
	v_mul_f32_e32 v60, v61, v60
	v_cvt_pk_bf16_f32 v60, v60, s0
	v_add_u32_e32 v61, 0x19200, v65
	ds_write_b16 v61, v60
	v_cmp_ge_i32_e32 vcc, v72, v71
	v_mov_b32_e32 v61, 0
	v_mov_b32_e32 v60, 0
	s_and_saveexec_b64 s[12:13], vcc
	v_mov_b32_e32 v60, v162
	s_nop 0
	v_sub_f32_e32 v60, v60, v0
	v_mul_f32_e32 v60, 0x3fb8aa3b, v60
	v_exp_f32_e32 v60, v60
.LBB0_691:
	s_or_b64 exec, exec, s[12:13]
	v_cmp_gt_i32_e32 vcc, v72, v71
	s_and_saveexec_b64 s[12:13], vcc
	v_mov_b32_e32 v61, v166
	s_nop 0
	v_mul_f32_e32 v61, v66, v61
	v_mul_f32_e32 v61, v60, v61

.LBB0_695:
	v_mul_f32_e32 v60, v62, v60
	v_cvt_pk_bf16_f32 v60, v60, s0
	v_add_u32_e32 v61, 0x19200, v64
	ds_write_b16 v61, v60
	v_cmp_ge_i32_e32 vcc, v73, v71
	v_mov_b32_e32 v60, 0
	v_mov_b32_e32 v61, 0
	s_and_saveexec_b64 s[0:1], vcc
	v_mov_b32_e32 v1, v163
	s_nop 0
	v_sub_f32_e32 v0, v1, v0
	v_mul_f32_e32 v0, 0x3fb8aa3b, v0
	v_exp_f32_e32 v61, v0
.LBB0_697:
	s_or_b64 exec, exec, s[0:1]
	v_cmp_gt_i32_e32 vcc, v73, v71
	s_and_saveexec_b64 s[0:1], vcc
	s_waitcnt lgkmcnt(6)
	v_mov_b32_e32 v0, v167
	s_nop 0
	v_mul_f32_e32 v0, v67, v0
	v_mul_f32_e32 v60, v61, v0

.LBB0_705:
	v_mov_b32_e32 v0, s60
	v_cndmask_b32_e64 v155, v111, v0, s[6:7]
	s_add_i32 s18, 16, 0x21000
	s_add_i32 s19, 16, 0x8800
	v_mov_b32_e32 v3, v120
	v_mov_b32_e32 v0, v107
	v_mov_b32_e32 v74, v121
	s_and_b64 s[0:1], s[14:15], exec
	s_waitcnt lgkmcnt(0)
	s_barrier
	s_cselect_b32 s0, s19, s18
	v_mul_lo_u32 v0, v3, s24
	s_add_i32 s1, 16, 0x16400
	v_lshlrev_b32_e32 v68, 3, v74
	v_add3_u32 v0, s1, v0, v68
	v_add_u32_e32 v1, 0x1000, v0
	v_mul_lo_u32 v69, v3, 40
	v_lshl_add_u32 v3, v3, 1, s43
	v_mul_lo_u32 v74, v74, s25
	ds_read_b64 v[64:65], v1 offset:512
	ds_read_b64 v[66:67], v1 offset:544
	v_add_u32_e32 v1, 0x1800, v0
	v_add3_u32 v68, s40, v68, v69
	v_add_u32_e32 v156, v3, v74
	ds_read_b64 v[72:73], v0 offset:2304
	ds_read_b64 v[60:61], v1 offset:768
	ds_read_b64 v[62:63], v1 offset:800
	ds_read_b64 v[0:1], v0 offset:6976
	ds_read_b64 v[84:85], v68
	ds_read_b64 v[86:87], v68 offset:640
	ds_read_b64 v[70:71], v68 offset:1920
	ds_read_b64 v[68:69], v68 offset:1280
	ds_read_u16 v188, v156 offset:61696
	v_add_u32_e32 v75, 0xd000, v3
	v_add_u32_e32 v101, 0x6510, v74
	v_add_u32_e32 v162, v75, v101
	ds_read_u16 v77, v162
	ds_read_u16 v189, v156 offset:62224
	v_add_u32_e32 v102, 0x6720, v74
	v_add_u32_e32 v163, v75, v102
	ds_read_u16 v78, v163
	v_add_u32_e32 v100, 0x6300, v74
	ds_read_u16 v190, v156 offset:62752
	v_add_u32_e32 v96, 0x4200, v74
	v_add_u32_e32 v97, 0x4410, v74
	v_add_u32_e32 v98, 0x4620, v74
	v_add_u32_e32 v99, 0x4830, v74
	v_add_u32_e32 v74, 0x6930, v74
	v_add_u32_e32 v164, v75, v74
	v_add_u32_e32 v157, v75, v96
	v_add_u32_e32 v158, v75, v97
	v_add_u32_e32 v159, v75, v98
	v_add_u32_e32 v160, v75, v99
	v_add_u32_e32 v161, v75, v100
	ds_read_u16 v192, v164
	ds_read_u16 v191, v156 offset:63280
	v_add_u32_e32 v75, 0xd020, v3
	ds_read_u16 v193, v157
	v_add_u32_e32 v181, v75, v97
	v_add_u32_e32 v185, v75, v101
	v_add_u32_e32 v182, v75, v98
	v_add_u32_e32 v186, v75, v102
	ds_read_u16 v194, v158
	v_add_u32_e32 v180, v75, v96
	v_add_u32_e32 v183, v75, v99
	v_add_u32_e32 v184, v75, v100
	v_add_u32_e32 v187, v75, v74
	ds_read_u16 v195, v159
	ds_read_u16 v196, v160
	ds_read_u16 v76, v161
	s_waitcnt lgkmcnt(1)
	v_lshlrev_b32_e32 v88, 16, v188
	v_lshlrev_b32_e32 v89, 16, v189
	v_lshlrev_b32_e32 v90, 16, v190
	v_lshlrev_b32_e32 v77, 16, v77
	v_lshlrev_b32_e32 v78, 16, v78
	v_lshlrev_b32_e32 v79, 16, v192
	v_lshlrev_b32_e32 v91, 16, v191
	v_lshlrev_b32_e32 v80, 16, v193
	v_lshlrev_b32_e32 v81, 16, v194
	v_lshlrev_b32_e32 v82, 16, v195
	v_lshlrev_b32_e32 v83, 16, v196
	ds_read_u16 v168, v156 offset:53248
	ds_read_u16 v3, v156 offset:53280
	ds_read_u16 v197, v156 offset:53808
	ds_read_u16 v93, v156 offset:62256
	ds_read_u16 v97, v181
	ds_read_u16 v101, v185
	ds_read_u16 v94, v156 offset:62784
	ds_read_u16 v98, v182
	ds_read_u16 v102, v186
	ds_read_u16 v198, v156 offset:54336
	ds_read_u16 v95, v156 offset:63312
	ds_read_u16 v99, v183
	ds_read_u16 v74, v187
	ds_read_u16 v96, v180
	ds_read_u16 v100, v184
	ds_read_u16 v199, v156 offset:54864
	ds_read_u16 v92, v156 offset:61728
	ds_read_u16 v169, v156 offset:54832
	ds_read_u16 v170, v156 offset:53776
	ds_read_u16 v171, v156 offset:54304
	s_waitcnt lgkmcnt(13)
	v_lshlrev_b32_e32 v3, 16, v3
	v_lshlrev_b32_e32 v76, 16, v76
	v_lshlrev_b32_e32 v93, 16, v93
	v_lshlrev_b32_e32 v94, 16, v94
	s_waitcnt lgkmcnt(6)
	v_lshlrev_b32_e32 v95, 16, v95
	v_lshlrev_b32_e32 v96, 16, v96
	v_lshlrev_b32_e32 v97, 16, v97
	s_waitcnt lgkmcnt(3)
	v_lshlrev_b32_e32 v92, 16, v92
	v_lshlrev_b32_e32 v98, 16, v98
	v_lshlrev_b32_e32 v99, 16, v99
	v_lshlrev_b32_e32 v100, 16, v100
	v_lshlrev_b32_e32 v101, 16, v101
	v_lshlrev_b32_e32 v102, 16, v102
	v_lshlrev_b32_e32 v103, 16, v74
	v_lshlrev_b32_e32 v165, 16, v197
	v_lshlrev_b32_e32 v166, 16, v198
	v_lshlrev_b32_e32 v167, 16, v199
	v_mov_b32_e32 v140, v84
	v_mov_b32_e32 v141, v85
	v_mov_b32_e32 v142, v2
	v_mov_b32_e32 v143, v2
	s_waitcnt lgkmcnt(2)
	v_lshlrev_b32_e32 v84, 16, v169
	v_lshlrev_b32_e32 v85, 16, v168
	s_waitcnt lgkmcnt(1)
	v_lshlrev_b32_e32 v168, 16, v170
	s_waitcnt lgkmcnt(0)
	v_lshlrev_b32_e32 v169, 16, v171
	v_cvt_pk_bf16_f32 v169, v169, v84
	v_cvt_pk_bf16_f32 v168, v85, v168
	v_mov_b32_e32 v170, v2
	v_mov_b32_e32 v171, v2
	v_mov_b32_e32 v74, v2
	v_mov_b32_e32 v75, v2
	v_mfma_f32_16x16x32_bf16 v[168:171], v[140:143], v[168:171], 0
	v_cvt_pk_bf16_f32 v173, v166, v167
	v_cvt_pk_bf16_f32 v172, v3, v165
	v_mov_b32_e32 v174, v2
	v_mov_b32_e32 v175, v2
	v_mov_b32_e32 v84, v86
	v_mov_b32_e32 v85, v87
	v_mfma_f32_16x16x32_bf16 v[140:143], v[140:143], v[172:175], 0
	s_nop 0
	v_cvt_pk_bf16_f32 v173, v170, v171
	v_cvt_pk_bf16_f32 v172, v168, v169
	v_mov_b32_e32 v86, v2
	v_mov_b32_e32 v87, v2
	v_mfma_f32_16x16x32_bf16 v[88:91], v[72:75], v[172:175], v[88:91]
	v_mov_b32_e32 v176, v2
	v_mov_b32_e32 v177, v2
	v_mov_b32_e32 v178, v2
	v_mov_b32_e32 v179, v2
	v_mov_b32_e32 v3, v2
	s_nop 2
	v_cvt_pk_bf16_f32 v175, v90, v91
	v_cvt_pk_bf16_f32 v174, v88, v89
	s_cmp_lg_u32 16, -1
	s_cselect_b32 s1, s41, 0
	v_mfma_f32_16x16x32_bf16 v[88:91], v[84:87], v[174:177], 0
	v_cvt_pk_bf16_f32 v177, v142, v143
	v_cvt_pk_bf16_f32 v176, v140, v141
	s_nop 1
	v_mfma_f32_16x16x32_bf16 v[72:75], v[72:75], v[176:179], v[92:95]
	s_nop 2
	v_cvt_pk_bf16_f32 v175, v90, v91
	v_cvt_pk_bf16_f32 v174, v88, v89
	v_mov_b32_e32 v94, v2
	v_mov_b32_e32 v95, v2
	s_nop 0
	v_cvt_pk_bf16_f32 v93, v74, v75
	v_cvt_pk_bf16_f32 v92, v72, v73
	v_mfma_f32_16x16x32_bf16 v[80:83], v[64:67], v[172:175], v[80:83]
	s_nop 0
	v_mfma_f32_16x16x32_bf16 v[72:75], v[84:87], v[92:95], 0
	v_mov_b32_e32 v84, v68
	v_mov_b32_e32 v85, v69
	s_nop 3
	v_cvt_pk_bf16_f32 v93, v82, v83
	v_cvt_pk_bf16_f32 v92, v80, v81
	v_mfma_f32_16x16x32_bf16 v[76:79], v[60:63], v[172:175], v[76:79]
	v_cvt_pk_bf16_f32 v179, v74, v75
	v_cvt_pk_bf16_f32 v178, v72, v73
	v_mov_b32_e32 v68, v2
	v_mfma_f32_16x16x32_bf16 v[80:83], v[84:87], v[92:95], 0
	v_mov_b32_e32 v69, v2
	v_mfma_f32_16x16x32_bf16 v[64:67], v[64:67], v[176:179], v[96:99]
	v_mfma_f32_16x16x32_bf16 v[60:63], v[60:63], v[176:179], v[100:103]
	s_nop 6
	v_cvt_pk_bf16_f32 v67, v66, v67
	v_cvt_pk_bf16_f32 v66, v64, v65
	s_nop 1
	v_mfma_f32_16x16x32_bf16 v[64:67], v[84:87], v[66:69], 0
	v_cvt_pk_bf16_f32 v85, v82, v83
	v_cvt_pk_bf16_f32 v84, v80, v81
	v_mov_b32_e32 v68, v70
	v_mov_b32_e32 v69, v71
	v_mov_b32_e32 v70, v2
	v_mov_b32_e32 v71, v2
	v_mfma_f32_16x16x32_bf16 v[76:79], v[0:3], v[84:87], v[76:79]
	s_nop 7
	v_cvt_pk_bf16_f32 v85, v78, v79
	v_cvt_pk_bf16_f32 v84, v76, v77
	s_nop 1
	v_mfma_f32_16x16x32_bf16 v[76:79], v[68:71], v[84:87], 0
	v_cvt_pk_bf16_f32 v85, v66, v67
	v_cvt_pk_bf16_f32 v84, v64, v65
	s_nop 1
	v_mfma_f32_16x16x32_bf16 v[60:63], v[0:3], v[84:87], v[60:63]
	v_cvt_pk_bf16_f32 v87, v30, v31
	v_cvt_pk_bf16_f32 v86, v28, v29
	v_cvt_pk_bf16_f32 v85, v34, v35
	v_cvt_pk_bf16_f32 v84, v32, v33
	s_nop 3
	v_cvt_pk_bf16_f32 v1, v62, v63
	v_cvt_pk_bf16_f32 v0, v60, v61
	s_nop 1
	v_mfma_f32_16x16x32_bf16 v[60:63], v[68:71], v[0:3], 0
	v_cvt_pk_bf16_f32 v0, v168, s0
	ds_write_b16 v156, v0 offset:53248
	v_cvt_pk_bf16_f32 v0, v169, s0
	ds_write_b16 v156, v0 offset:53776
	v_cvt_pk_bf16_f32 v0, v170, s0
	ds_write_b16 v156, v0 offset:54304
	v_cvt_pk_bf16_f32 v0, v171, s0
	ds_write_b16 v156, v0 offset:54832
	v_cvt_pk_bf16_f32 v0, v88, s0
	ds_write_b16 v156, v0 offset:61696
	v_cvt_pk_bf16_f32 v0, v89, s0
	ds_write_b16 v156, v0 offset:62224
	v_cvt_pk_bf16_f32 v0, v90, s0
	ds_write_b16 v156, v0 offset:62752
	v_cvt_pk_bf16_f32 v0, v91, s0
	ds_write_b16 v156, v0 offset:63280
	v_cvt_pk_bf16_f32 v0, v80, s0
	ds_write_b16 v157, v0
	v_cvt_pk_bf16_f32 v0, v81, s0
	ds_write_b16 v158, v0
	v_cvt_pk_bf16_f32 v0, v82, s0
	ds_write_b16 v159, v0
	v_cvt_pk_bf16_f32 v0, v83, s0
	ds_write_b16 v160, v0
	v_cvt_pk_bf16_f32 v0, v76, s0
	ds_write_b16 v161, v0
	v_cvt_pk_bf16_f32 v0, v77, s0
	ds_write_b16 v162, v0
	v_cvt_pk_bf16_f32 v0, v78, s0
	ds_write_b16 v163, v0
	v_cvt_pk_bf16_f32 v0, v79, s0
	ds_write_b16 v164, v0
	v_cvt_pk_bf16_f32 v0, v140, s0
	ds_write_b16 v156, v0 offset:53280
	v_cvt_pk_bf16_f32 v0, v141, s0
	ds_write_b16 v156, v0 offset:53808
	v_cvt_pk_bf16_f32 v0, v142, s0
	ds_write_b16 v156, v0 offset:54336
	v_cvt_pk_bf16_f32 v0, v143, s0
	ds_write_b16 v156, v0 offset:54864
	v_cvt_pk_bf16_f32 v0, v72, s0
	ds_write_b16 v156, v0 offset:61728
	v_cvt_pk_bf16_f32 v0, v73, s0
	ds_write_b16 v156, v0 offset:62256
	v_cvt_pk_bf16_f32 v0, v74, s0
	ds_write_b16 v156, v0 offset:62784
	v_cvt_pk_bf16_f32 v0, v75, s0
	ds_write_b16 v156, v0 offset:63312
	v_cvt_pk_bf16_f32 v0, v64, s0
	ds_write_b16 v180, v0
	v_cvt_pk_bf16_f32 v0, v65, s0
	ds_write_b16 v181, v0
	v_cvt_pk_bf16_f32 v0, v66, s0
	ds_write_b16 v182, v0
	v_cvt_pk_bf16_f32 v0, v67, s0
	ds_write_b16 v183, v0
	v_cvt_pk_bf16_f32 v0, v60, s0
	ds_write_b16 v184, v0
	v_cvt_pk_bf16_f32 v0, v61, s0
	ds_write_b16 v185, v0
	v_cvt_pk_bf16_f32 v0, v62, s0
	ds_write_b16 v186, v0
	v_cvt_pk_bf16_f32 v0, v63, s0
	v_mov_b32_e32 v3, v107
	v_mov_b32_e32 v88, v120
	v_mov_b32_e32 v89, v121
	ds_write_b16 v187, v0
	s_waitcnt lgkmcnt(0)
	s_barrier
	v_cvt_pk_bf16_f32 v63, v6, v7
	v_mul_lo_u32 v0, v88, s22
	v_lshlrev_b32_e32 v90, 3, v89
	v_add3_u32 v164, 16, v0, v90
	v_add_u32_e32 v0, 0xd000, v164
	ds_read_b64 v[72:73], v0 offset:256
	ds_read_b64 v[74:75], v0 offset:288
	ds_read_b64 v[76:77], v0 offset:320
	ds_read_b64 v[78:79], v0 offset:352
	v_cvt_pk_bf16_f32 v62, v4, v5
	v_cvt_pk_bf16_f32 v61, v10, v11
	v_cvt_pk_bf16_f32 v60, v8, v9
	ds_read_b64 v[80:81], v0 offset:384
	ds_read_b64 v[82:83], v0 offset:416
	v_cvt_pk_bf16_f32 v67, v14, v15
	s_waitcnt lgkmcnt(4)
	v_mfma_f32_16x16x32_bf16 v[72:75], v[72:75], v[60:63], 0
	v_cvt_pk_bf16_f32 v66, v12, v13
	v_cvt_pk_bf16_f32 v65, v18, v19
	v_cvt_pk_bf16_f32 v64, v16, v17
	ds_read_b64 v[92:93], v0 offset:448
	ds_read_b64 v[94:95], v0 offset:480
	v_mul_lo_u32 v0, v88, s21
	s_waitcnt lgkmcnt(4)
	v_mfma_f32_16x16x32_bf16 v[72:75], v[76:79], v[64:67], v[72:75]
	v_cvt_pk_bf16_f32 v71, v22, v23
	v_cvt_pk_bf16_f32 v70, v20, v21
	v_cvt_pk_bf16_f32 v69, v26, v27
	v_cvt_pk_bf16_f32 v68, v24, v25
	v_add3_u32 v165, s66, v90, v0
	ds_read_b64 v[76:77], v165
	ds_read_b64 v[78:79], v165 offset:32
	s_waitcnt lgkmcnt(4)
	v_mfma_f32_16x16x32_bf16 v[72:75], v[80:83], v[68:71], v[72:75]
	v_add_u32_e32 v1, 0xf000, v164
	ds_read_b64 v[98:99], v1 offset:640
	ds_read_b64 v[100:101], v1 offset:672
	v_add_u32_e32 v91, 0x1000, v165
	s_waitcnt lgkmcnt(4)
	v_mfma_f32_16x16x32_bf16 v[80:83], v[92:95], v[84:87], v[72:75]
	ds_read_b64 v[92:93], v165 offset:128
	ds_read_b64 v[94:95], v165 offset:160
	v_lshl_add_u32 v0, v88, 1, s61
	v_mad_u64_u32 v[102:103], s[12:13], v89, s25, v[0:1]
	ds_read_b64 v[72:73], v165 offset:64
	ds_read_b64 v[74:75], v165 offset:96
	s_waitcnt lgkmcnt(6)
	v_mfma_f32_16x16x32_bf16 v[76:79], v[76:79], v[60:63], 0
	s_waitcnt lgkmcnt(0)
	v_mfma_f32_16x16x32_bf16 v[72:75], v[72:75], v[64:67], v[76:79]
	s_nop 5
	ds_read_b64 v[76:77], v165 offset:192
	ds_read_b64 v[78:79], v165 offset:224
	v_mfma_f32_16x16x32_bf16 v[72:75], v[92:95], v[68:71], v[72:75]
	ds_read_b64 v[94:95], v1 offset:512
	ds_read_b64 v[96:97], v1 offset:544
	v_lshlrev_b32_e32 v92, 2, v89
	v_or_b32_e32 v176, 1, v92
	s_waitcnt lgkmcnt(2)
	v_mfma_f32_16x16x32_bf16 v[72:75], v[76:79], v[84:87], v[72:75]
	ds_read_b64 v[76:77], v1 offset:576
	ds_read_b64 v[78:79], v1 offset:608
	v_mad_u64_u32 v[160:161], s[12:13], v176, s22, v[0:1]
	s_waitcnt lgkmcnt(2)
	v_mfma_f32_16x16x32_bf16 v[94:97], v[94:97], v[60:63], 0
	v_add_u32_e32 v172, 0x1ef0, v160
	s_cselect_b32 s12, 16, 0
	s_add_u32 s12, s12, 0x1c8fc
	s_waitcnt lgkmcnt(0)
	v_mfma_f32_16x16x32_bf16 v[76:79], v[76:79], v[64:67], v[94:97]
	s_addc_u32 s13, s1, 0
	s_nop 1
	ds_read_b64 v[94:95], v91 offset:256
	ds_read_b64 v[96:97], v91 offset:288
	s_cmp_lg_u64 s[12:13], 0
	v_mfma_f32_16x16x32_bf16 v[76:79], v[98:101], v[68:71], v[76:79]
	ds_read_b64 v[98:99], v1 offset:704
	ds_read_b64 v[100:101], v1 offset:736
	ds_read_u16 v0, v102 offset:53248
	ds_read_u16 v1, v160 offset:53248
	ds_read_u16 v93, v160 offset:53776
	ds_read_u16 v102, v160 offset:54304
	ds_read_u16 v161, v160 offset:61168
	ds_read_u16 v162, v160 offset:61696
	ds_read_u16 v166, v160 offset:62224
	ds_read_u16 v167, v160 offset:62752
	ds_read_b64 v[140:141], v91 offset:320
	ds_read_b64 v[142:143], v91 offset:352
	s_waitcnt lgkmcnt(8)
	v_lshlrev_b32_e32 v1, 16, v1
	v_mfma_f32_16x16x32_bf16 v[94:97], v[94:97], v[60:63], 0
	v_lshlrev_b32_e32 v0, 16, v0
	v_pk_add_f32 v[0:1], v[0:1], v[80:81] neg_lo:[0,1] neg_hi:[0,1]
	v_add_u32_e32 v80, 0x4200, v164
	v_mfma_f32_16x16x32_bf16 v[98:101], v[98:101], v[84:87], v[76:79]
	v_add_u32_e32 v168, 0xd000, v80
	s_waitcnt lgkmcnt(6)
	v_lshlrev_b32_e32 v81, 16, v102
	ds_read_b64 v[156:157], v91 offset:448
	ds_read_b64 v[158:159], v91 offset:480
	ds_read_b64 v[76:77], v91 offset:384
	ds_read_b64 v[78:79], v91 offset:416
	s_waitcnt lgkmcnt(4)
	v_mfma_f32_16x16x32_bf16 v[94:97], v[140:143], v[64:67], v[94:97]
	ds_read_b64 v[140:141], v168 offset:256
	ds_read_b64 v[142:143], v168 offset:288
	v_lshlrev_b32_e32 v80, 16, v93
	v_pk_add_f32 v[102:103], v[80:81], v[82:83] neg_lo:[0,1] neg_hi:[0,1]
	ds_read_b64 v[80:81], v168 offset:320
	ds_read_b64 v[82:83], v168 offset:352
	s_waitcnt lgkmcnt(4)
	v_mfma_f32_16x16x32_bf16 v[76:79], v[76:79], v[68:71], v[94:97]
	s_nop 2
	ds_read_b64 v[94:95], v168 offset:384
	ds_read_b64 v[96:97], v168 offset:416
	v_add_u32_e32 v93, 0x2000, v165
	v_lshlrev_b32_e32 v163, 16, v162
	s_waitcnt lgkmcnt(4)
	v_mfma_f32_16x16x32_bf16 v[140:143], v[140:143], v[60:63], 0
	v_lshlrev_b32_e32 v162, 16, v161
	v_add_u32_e32 v165, 0x3000, v165
	s_cselect_b32 s1, s12, -1
	v_mfma_f32_16x16x32_bf16 v[76:79], v[156:159], v[84:87], v[76:79]
	ds_read_b64 v[156:157], v168 offset:448
	ds_read_b64 v[158:159], v168 offset:480
	v_pk_add_f32 v[168:169], v[162:163], v[98:99] neg_lo:[0,1] neg_hi:[0,1]
	v_lshlrev_b32_e32 v99, 16, v167
	s_waitcnt lgkmcnt(4)
	v_mfma_f32_16x16x32_bf16 v[80:83], v[80:83], v[64:67], v[140:143]
	v_lshlrev_b32_e32 v98, 16, v166
	v_pk_add_f32 v[170:171], v[98:99], v[100:101] neg_lo:[0,1] neg_hi:[0,1]
	ds_read_b64 v[98:99], v93 offset:704
	ds_read_b64 v[100:101], v93 offset:736
	ds_read_b64 v[140:141], v93 offset:512
	ds_read_b64 v[142:143], v93 offset:544
	s_waitcnt lgkmcnt(6)
	v_mfma_f32_16x16x32_bf16 v[80:83], v[94:97], v[68:71], v[80:83]
	ds_read_b64 v[94:95], v93 offset:576
	ds_read_b64 v[96:97], v93 offset:608
	s_add_i32 s66, 16, 0x258fc
	s_and_b64 s[12:13], s[14:15], exec
	s_waitcnt lgkmcnt(6)
	v_mfma_f32_16x16x32_bf16 v[156:159], v[156:159], v[84:87], v[80:83]
	s_cselect_b32 s1, s1, s66
	v_or_b32_e32 v177, 2, v92
	v_or_b32_e32 v178, 3, v92
	ds_read_b64 v[80:81], v93 offset:640
	ds_read_b64 v[82:83], v93 offset:672
	s_waitcnt lgkmcnt(4)
	v_mfma_f32_16x16x32_bf16 v[140:143], v[140:143], v[60:63], 0
	v_add_u32_e32 v91, 16, v92
	v_add_u32_e32 v179, 17, v92
	v_add_u32_e32 v180, 18, v92
	s_waitcnt lgkmcnt(2)
	v_mfma_f32_16x16x32_bf16 v[94:97], v[94:97], v[64:67], v[140:143]
	v_add_u32_e32 v181, 19, v92
	v_add_u32_e32 v93, 32, v92
	v_add_u32_e32 v182, 33, v92
	s_waitcnt lgkmcnt(0)
	v_mfma_f32_16x16x32_bf16 v[80:83], v[80:83], v[68:71], v[94:97]
	v_add_u32_e32 v140, 0x3ff0, v160
	v_add_u32_e32 v187, 34, v92
	v_add_u32_e32 v188, 35, v92
	v_add_u32_e32 v94, 0x6300, v164
	v_add_u32_e32 v162, 0xd000, v94
	ds_read_b64 v[94:95], v162 offset:256
	ds_read_b64 v[96:97], v162 offset:288
	ds_read_u16 v160, v172 offset:61696
	ds_read_u16 v141, v172 offset:62224
	ds_read_u16 v164, v172 offset:62752
	ds_read_u16 v166, v172 offset:63280
	ds_read_u16 v183, v140 offset:61696
	ds_read_u16 v184, v140 offset:62224
	ds_read_u16 v185, v140 offset:62752
	ds_read_u16 v186, v140 offset:63280
	s_waitcnt lgkmcnt(6)
	v_lshlrev_b32_e32 v161, 16, v141
	ds_read_b64 v[140:141], v162 offset:320
	ds_read_b64 v[142:143], v162 offset:352
	v_mfma_f32_16x16x32_bf16 v[80:83], v[98:101], v[84:87], v[80:83]
	ds_read_b64 v[98:99], v162 offset:384
	ds_read_b64 v[100:101], v162 offset:416
	v_lshlrev_b32_e32 v160, 16, v160
	v_pk_add_f32 v[172:173], v[160:161], v[156:157] neg_lo:[0,1] neg_hi:[0,1]
	v_mfma_f32_16x16x32_bf16 v[94:97], v[94:97], v[60:63], 0
	ds_read_b64 v[160:161], v162 offset:448
	ds_read_b64 v[162:163], v162 offset:480
	s_waitcnt lgkmcnt(10)
	v_lshlrev_b32_e32 v157, 16, v166
	v_lshlrev_b32_e32 v156, 16, v164
	s_waitcnt lgkmcnt(4)
	v_mfma_f32_16x16x32_bf16 v[94:97], v[140:143], v[64:67], v[94:97]
	ds_read_b64 v[140:141], v165 offset:768
	ds_read_b64 v[142:143], v165 offset:800
	v_pk_add_f32 v[174:175], v[156:157], v[158:159] neg_lo:[0,1] neg_hi:[0,1]
	v_add_u32_e32 v189, 49, v92
	s_waitcnt lgkmcnt(4)
	v_mfma_f32_16x16x32_bf16 v[94:97], v[98:101], v[68:71], v[94:97]
	ds_read_b64 v[98:99], v165 offset:832
	ds_read_b64 v[100:101], v165 offset:864
	s_add_i32 s60, s60, 1
	v_cmp_lt_u32_e32 vcc, s60, v109
	s_waitcnt lgkmcnt(2)
	v_mfma_f32_16x16x32_bf16 v[60:63], v[140:143], v[60:63], 0
	v_mfma_f32_16x16x32_bf16 v[156:159], v[160:163], v[84:87], v[94:97]
	ds_read_b64 v[160:161], v165 offset:896
	ds_read_b64 v[162:163], v165 offset:928
	ds_read_b64 v[166:167], v165 offset:992
	ds_read_b64 v[164:165], v165 offset:960
	s_nop 0
	v_lshlrev_b32_e32 v97, 16, v184
	s_waitcnt lgkmcnt(4)
	v_mfma_f32_16x16x32_bf16 v[60:63], v[98:101], v[64:67], v[60:63]
	v_lshlrev_b32_e32 v65, 16, v186
	v_lshlrev_b32_e32 v64, 16, v185
	v_lshlrev_b32_e32 v96, 16, v183
	s_waitcnt lgkmcnt(2)
	v_mfma_f32_16x16x32_bf16 v[60:63], v[160:163], v[68:71], v[60:63]
	v_add_f32_e64 v64, v64, -v158
	v_add_f32_e64 v65, v65, -v159
	v_mul_lo_u32 v159, v88, s24
	v_pk_add_f32 v[96:97], v[96:97], v[156:157] neg_lo:[0,1] neg_hi:[0,1]
	s_waitcnt lgkmcnt(0)
	v_mfma_f32_16x16x32_bf16 v[68:71], v[164:167], v[84:87], v[60:63]
	v_cvt_pk_bf16_f32 v66, v96, v97
	v_cvt_pk_bf16_f32 v67, v64, v65
	v_cvt_pk_bf16_f32 v65, v174, v175
	v_cvt_pk_bf16_f32 v60, v0, v1
	v_mov_b32_e32 v0, s1
	s_add_i32 s1, 16, 0x19200
	v_add_u32_e32 v158, s1, v90
	v_add_u32_e32 v84, v158, v159
	ds_read_b64 v[96:97], v84
	ds_read_b64 v[98:99], v84 offset:32
	ds_read_b32 v0, v0
	v_cvt_pk_bf16_f32 v61, v102, v103
	ds_read_b64 v[100:101], v84 offset:64
	ds_read_b64 v[102:103], v84 offset:96
	v_cvt_pk_bf16_f32 v63, v170, v171
	v_cvt_pk_bf16_f32 v62, v168, v169
	s_waitcnt lgkmcnt(2)
	v_mul_f32_e32 v157, 0x3fb8aa3b, v0
	v_lshlrev_b32_e32 v0, 6, v155
	v_lshl_add_u32 v155, v89, 4, s65
	ds_read_b128 v[140:143], v155
	v_ashrrev_i32_e32 v89, 31, v88
	v_lshl_add_u64 v[84:85], v[88:89], 2, v[116:117]
	v_mfma_f32_16x16x32_bf16 v[86:89], v[96:99], v[60:63], 0
	v_cvt_pk_bf16_f32 v64, v172, v173
	ds_read_b128 v[96:99], v155 offset:64
	s_waitcnt lgkmcnt(1)
	v_mul_f32_e32 v140, 0x3fb8aa3b, v140
	v_exp_f32_e32 v140, v140
	v_mfma_f32_16x16x32_bf16 v[86:89], v[100:103], v[64:67], v[86:89]
	v_sub_u32_e32 v100, 63, v92
	v_ashrrev_i32_e32 v1, 31, v0
	v_cndmask_b32_e64 v100, v100, v92, s[6:7]
	v_lshl_add_u64 v[0:1], v[0:1], 0, v[104:105]
	v_ashrrev_i32_e32 v101, 31, v100
	s_nop 2
	v_fma_f32 v72, v72, v140, v86
	v_lshl_add_u64 v[100:101], v[0:1], 0, v[100:101]
	v_mul_f32_e32 v86, 0x3fb8aa3b, v141
	v_lshlrev_b64 v[100:101], 12, v[100:101]
	v_exp_f32_e32 v86, v86
	v_lshl_add_u64 v[100:101], v[84:85], 0, v[100:101]
	global_store_dword v[100:101], v72, off
	v_sub_u32_e32 v72, 63, v176
	v_cndmask_b32_e64 v72, v72, v176, s[6:7]
	v_fma_f32 v86, v73, v86, v87
	v_ashrrev_i32_e32 v73, 31, v72
	v_lshl_add_u64 v[72:73], v[0:1], 0, v[72:73]
	v_lshlrev_b64 v[72:73], 12, v[72:73]
	v_lshl_add_u64 v[72:73], v[84:85], 0, v[72:73]
	v_mul_f32_e32 v87, 0x3fb8aa3b, v142
	global_store_dword v[72:73], v86, off
	v_sub_u32_e32 v72, 63, v177
	v_exp_f32_e32 v87, v87
	v_cndmask_b32_e64 v72, v72, v177, s[6:7]
	v_ashrrev_i32_e32 v73, 31, v72
	v_lshl_add_u64 v[72:73], v[0:1], 0, v[72:73]
	v_lshlrev_b64 v[72:73], 12, v[72:73]
	v_fma_f32 v74, v74, v87, v88
	v_lshl_add_u64 v[72:73], v[84:85], 0, v[72:73]
	v_add_u32_e32 v140, 0x900, v159
	global_store_dword v[72:73], v74, off
	v_mul_f32_e32 v72, 0x3fb8aa3b, v143
	v_add_u32_e32 v73, v158, v140
	v_exp_f32_e32 v72, v72
	ds_read_b64 v[100:101], v73
	ds_read_b64 v[102:103], v73 offset:32
	v_sub_u32_e32 v74, 63, v178
	v_cndmask_b32_e64 v86, v74, v178, s[6:7]
	v_fmac_f32_e32 v89, v75, v72
	ds_read_b64 v[74:75], v73 offset:96
	ds_read_b64 v[72:73], v73 offset:64
	v_ashrrev_i32_e32 v87, 31, v86
	v_lshl_add_u64 v[86:87], v[0:1], 0, v[86:87]
	s_waitcnt lgkmcnt(2)
	v_mfma_f32_16x16x32_bf16 v[100:103], v[100:103], v[60:63], 0
	v_lshlrev_b64 v[86:87], 12, v[86:87]
	v_lshl_add_u64 v[86:87], v[84:85], 0, v[86:87]
	global_store_dword v[86:87], v89, off
	v_mul_f32_e32 v86, 0x3fb8aa3b, v96
	v_exp_f32_e32 v87, v86
	s_waitcnt lgkmcnt(0)
	v_mfma_f32_16x16x32_bf16 v[72:75], v[72:75], v[64:67], v[100:103]
	v_sub_u32_e32 v86, 47, v92
	v_cndmask_b32_e64 v86, v86, v91, s[6:7]
	v_add_u32_e32 v141, 0x1200, v159
	ds_read_b128 v[100:103], v155 offset:128
	v_add_u32_e32 v94, 48, v92
	s_nop 2
	v_fma_f32 v72, v76, v87, v72
	v_ashrrev_i32_e32 v87, 31, v86
	v_lshl_add_u64 v[86:87], v[0:1], 0, v[86:87]
	v_mul_f32_e32 v76, 0x3fb8aa3b, v97
	v_lshlrev_b64 v[86:87], 12, v[86:87]
	v_exp_f32_e32 v76, v76
	v_lshl_add_u64 v[86:87], v[84:85], 0, v[86:87]
	global_store_dword v[86:87], v72, off
	v_sub_u32_e32 v72, 46, v92
	v_cndmask_b32_e64 v72, v72, v179, s[6:7]
	v_fma_f32 v76, v77, v76, v73
	v_ashrrev_i32_e32 v73, 31, v72
	v_lshl_add_u64 v[72:73], v[0:1], 0, v[72:73]
	v_lshlrev_b64 v[72:73], 12, v[72:73]
	v_lshl_add_u64 v[72:73], v[84:85], 0, v[72:73]
	v_mul_f32_e32 v77, 0x3fb8aa3b, v98
	global_store_dword v[72:73], v76, off
	v_sub_u32_e32 v72, 45, v92
	v_exp_f32_e32 v77, v77
	v_cndmask_b32_e64 v72, v72, v180, s[6:7]
	v_ashrrev_i32_e32 v73, 31, v72
	v_lshl_add_u64 v[72:73], v[0:1], 0, v[72:73]
	v_lshlrev_b64 v[72:73], 12, v[72:73]
	v_fma_f32 v74, v78, v77, v74
	v_lshl_add_u64 v[72:73], v[84:85], 0, v[72:73]
	global_store_dword v[72:73], v74, off
	v_add_u32_e32 v74, v158, v141
	v_mul_f32_e32 v73, 0x3fb8aa3b, v99
	ds_read_b64 v[86:87], v74
	ds_read_b64 v[88:89], v74 offset:32
	v_exp_f32_e32 v73, v73
	v_sub_u32_e32 v72, 44, v92
	v_cndmask_b32_e64 v72, v72, v181, s[6:7]
	ds_read_b64 v[96:97], v74 offset:64
	ds_read_b64 v[98:99], v74 offset:96
	v_fmac_f32_e32 v75, v79, v73
	v_ashrrev_i32_e32 v73, 31, v72
	v_lshl_add_u64 v[72:73], v[0:1], 0, v[72:73]
	v_lshlrev_b64 v[72:73], 12, v[72:73]
	v_lshl_add_u64 v[72:73], v[84:85], 0, v[72:73]
	global_store_dword v[72:73], v75, off
	s_waitcnt lgkmcnt(2)
	v_mfma_f32_16x16x32_bf16 v[72:75], v[86:89], v[60:63], 0
	ds_read_b128 v[76:79], v155 offset:192
	v_mul_f32_e32 v86, 0x3fb8aa3b, v100
	v_exp_f32_e32 v87, v86
	s_waitcnt lgkmcnt(1)
	v_mfma_f32_16x16x32_bf16 v[72:75], v[96:99], v[64:67], v[72:75]
	v_sub_u32_e32 v86, 31, v92
	v_cndmask_b32_e64 v86, v86, v93, s[6:7]
	v_add_u32_e32 v100, 0x1b00, v159
	v_add_u32_e32 v156, 50, v92
	v_add_u32_e32 v95, 51, v92
	s_nop 2
	v_fma_f32 v72, v80, v87, v72
	v_ashrrev_i32_e32 v87, 31, v86
	v_lshl_add_u64 v[86:87], v[0:1], 0, v[86:87]
	v_mul_f32_e32 v80, 0x3fb8aa3b, v101
	v_lshlrev_b64 v[86:87], 12, v[86:87]
	v_exp_f32_e32 v80, v80
	v_lshl_add_u64 v[86:87], v[84:85], 0, v[86:87]
	global_store_dword v[86:87], v72, off
	v_sub_u32_e32 v72, 30, v92
	v_cndmask_b32_e64 v72, v72, v182, s[6:7]
	v_fma_f32 v80, v81, v80, v73
	v_ashrrev_i32_e32 v73, 31, v72
	v_lshl_add_u64 v[72:73], v[0:1], 0, v[72:73]
	v_lshlrev_b64 v[72:73], 12, v[72:73]
	v_lshl_add_u64 v[72:73], v[84:85], 0, v[72:73]
	v_mul_f32_e32 v81, 0x3fb8aa3b, v102
	global_store_dword v[72:73], v80, off
	v_sub_u32_e32 v72, 29, v92
	v_exp_f32_e32 v81, v81
	v_cndmask_b32_e64 v72, v72, v187, s[6:7]
	v_ashrrev_i32_e32 v73, 31, v72
	v_lshl_add_u64 v[72:73], v[0:1], 0, v[72:73]
	v_lshlrev_b64 v[72:73], 12, v[72:73]
	v_fma_f32 v74, v82, v81, v74
	v_lshl_add_u64 v[72:73], v[84:85], 0, v[72:73]
	global_store_dword v[72:73], v74, off
	v_mul_f32_e32 v72, 0x3fb8aa3b, v103
	v_add_u32_e32 v74, v158, v100
	v_exp_f32_e32 v73, v72
	ds_read_b64 v[86:87], v74
	ds_read_b64 v[88:89], v74 offset:32
	v_sub_u32_e32 v72, 28, v92
	v_cndmask_b32_e64 v72, v72, v188, s[6:7]
	v_fmac_f32_e32 v75, v83, v73
	ds_read_b64 v[80:81], v74 offset:64
	ds_read_b64 v[82:83], v74 offset:96
	v_ashrrev_i32_e32 v73, 31, v72
	v_lshl_add_u64 v[72:73], v[0:1], 0, v[72:73]
	s_waitcnt lgkmcnt(2)
	v_mfma_f32_16x16x32_bf16 v[86:89], v[86:89], v[60:63], 0
	v_lshlrev_b64 v[72:73], 12, v[72:73]
	v_lshl_add_u64 v[72:73], v[84:85], 0, v[72:73]
	global_store_dword v[72:73], v75, off
	v_mul_f32_e32 v72, 0x3fb8aa3b, v76
	v_exp_f32_e32 v76, v72
	s_waitcnt lgkmcnt(0)
	v_mfma_f32_16x16x32_bf16 v[72:75], v[80:83], v[64:67], v[86:89]
	v_sub_u32_e32 v80, 15, v92
	v_cndmask_b32_e64 v80, v80, v94, s[6:7]
	v_ashrrev_i32_e32 v81, 31, v80
	v_lshl_add_u64 v[80:81], v[0:1], 0, v[80:81]
	v_lshlrev_b64 v[80:81], 12, v[80:81]
	s_nop 2
	v_fma_f32 v68, v68, v76, v72
	v_mul_f32_e32 v72, 0x3fb8aa3b, v77
	v_exp_f32_e32 v72, v72
	v_lshl_add_u64 v[80:81], v[84:85], 0, v[80:81]
	global_store_dword v[80:81], v68, off
	v_sub_u32_e32 v68, 14, v92
	v_cndmask_b32_e64 v68, v68, v189, s[6:7]
	v_fma_f32 v72, v69, v72, v73
	v_ashrrev_i32_e32 v69, 31, v68
	v_add_u32_e32 v101, s0, v159
	v_lshl_add_u64 v[68:69], v[0:1], 0, v[68:69]
	v_add_u32_e32 v73, v101, v90
	v_lshlrev_b64 v[68:69], 12, v[68:69]
	ds_read_b64 v[80:81], v73
	ds_read_b64 v[82:83], v73 offset:32
	v_lshl_add_u64 v[68:69], v[84:85], 0, v[68:69]
	global_store_dword v[68:69], v72, off
	v_sub_u32_e32 v69, 13, v92
	v_cndmask_b32_e64 v72, v69, v156, s[6:7]
	v_mul_f32_e32 v69, 0x3fb8aa3b, v78
	v_exp_f32_e32 v68, v157
	v_exp_f32_e32 v69, v69
	v_xor_b32_e32 v77, 8, v91
	v_pk_mul_f32 v[8:9], v[8:9], v[68:69] op_sel_hi:[1,0]
	v_pk_mul_f32 v[10:11], v[10:11], v[68:69] op_sel_hi:[1,0]
	v_fma_f32 v69, v70, v69, v74
	v_add_u32_e32 v70, s0, v141
	s_waitcnt lgkmcnt(0)
	v_mfma_f32_16x16x32_bf16 v[8:11], v[80:83], v[60:63], v[8:11]
	ds_read_b64 v[80:81], v73 offset:64
	ds_read_b64 v[82:83], v73 offset:96
	v_add_u32_e32 v73, s0, v140
	v_xad_u32 v76, v90, 16, v73
	v_lshl_add_u32 v77, v77, 1, v73
	ds_read_b64 v[86:87], v76
	ds_read_b64 v[88:89], v77
	v_xor_b32_e32 v76, 8, v93
	v_lshl_add_u32 v76, v76, 1, v73
	v_xor_b32_e32 v77, 8, v94
	v_lshl_add_u32 v73, v77, 1, v73
	ds_read_b64 v[96:97], v76
	ds_read_b64 v[98:99], v73
	v_xad_u32 v74, v90, 32, v70
	v_xor_b32_e32 v76, 16, v91
	s_waitcnt lgkmcnt(4)
	v_mfma_f32_16x16x32_bf16 v[8:11], v[80:83], v[64:67], v[8:11]
	v_lshl_add_u32 v76, v76, 1, v70
	ds_read_b64 v[80:81], v74
	ds_read_b64 v[82:83], v76
	v_xor_b32_e32 v74, 16, v93
	v_xor_b32_e32 v76, 16, v94
	v_pk_mul_f32 v[4:5], v[4:5], v[68:69] op_sel_hi:[1,0]
	v_pk_mul_f32 v[6:7], v[6:7], v[68:69] op_sel_hi:[1,0]
	v_lshl_add_u32 v74, v74, 1, v70
	v_lshl_add_u32 v70, v76, 1, v70
	s_waitcnt lgkmcnt(4)
	v_mfma_f32_16x16x32_bf16 v[4:7], v[86:89], v[60:63], v[4:7]
	v_ashrrev_i32_e32 v73, 31, v72
	ds_read_b64 v[86:87], v74
	ds_read_b64 v[88:89], v70
	v_add_u32_e32 v70, s0, v100
	v_lshl_add_u64 v[72:73], v[0:1], 0, v[72:73]
	v_pk_mul_f32 v[16:17], v[16:17], v[68:69] op_sel_hi:[1,0]
	v_pk_mul_f32 v[18:19], v[18:19], v[68:69] op_sel_hi:[1,0]
	v_xad_u32 v74, v90, 48, v70
	v_xor_b32_e32 v76, 24, v91
	v_lshlrev_b64 v[72:73], 12, v[72:73]
	s_waitcnt lgkmcnt(2)
	v_mfma_f32_16x16x32_bf16 v[16:19], v[80:83], v[60:63], v[16:19]
	v_lshl_add_u32 v76, v76, 1, v70
	ds_read_b64 v[80:81], v74
	ds_read_b64 v[82:83], v76
	v_xor_b32_e32 v74, 24, v93
	v_lshl_add_u32 v74, v74, 1, v70
	v_xor_b32_e32 v76, 24, v94
	v_lshl_add_u64 v[72:73], v[84:85], 0, v[72:73]
	v_mfma_f32_16x16x32_bf16 v[4:7], v[96:99], v[64:67], v[4:7]
	v_lshl_add_u32 v70, v76, 1, v70
	ds_read_b64 v[96:97], v74
	ds_read_b64 v[98:99], v70
	global_store_dword v[72:73], v69, off
	v_xad_u32 v72, v90, 64, v101
	v_xor_b32_e32 v73, 32, v91
	v_mul_f32_e32 v70, 0x3fb8aa3b, v79
	v_lshl_add_u32 v73, v73, 1, v101
	ds_read_b64 v[76:77], v72 offset:9216
	ds_read_b64 v[78:79], v73 offset:9216
	v_pk_mul_f32 v[12:13], v[12:13], v[68:69] op_sel_hi:[1,0]
	v_pk_mul_f32 v[14:15], v[14:15], v[68:69] op_sel_hi:[1,0]
	v_xor_b32_e32 v72, 32, v93
	v_xor_b32_e32 v73, 32, v94
	v_exp_f32_e32 v70, v70
	s_waitcnt lgkmcnt(4)
	v_mfma_f32_16x16x32_bf16 v[12:15], v[80:83], v[60:63], v[12:15]
	v_sub_u32_e32 v69, 12, v92
	v_lshl_add_u32 v72, v72, 1, v101
	v_lshl_add_u32 v73, v73, 1, v101
	s_movk_i32 s0, 0x50
	v_pk_mul_f32 v[24:25], v[24:25], v[68:69] op_sel_hi:[1,0]
	v_pk_mul_f32 v[26:27], v[26:27], v[68:69] op_sel_hi:[1,0]
	ds_read_b64 v[80:81], v72 offset:9216
	ds_read_b64 v[82:83], v73 offset:9216
	v_xad_u32 v72, v90, s0, v101
	v_xor_b32_e32 v73, 40, v91
	s_waitcnt lgkmcnt(2)
	v_mfma_f32_16x16x32_bf16 v[24:27], v[76:79], v[60:63], v[24:27]
	v_lshl_add_u32 v73, v73, 1, v101
	ds_read_b64 v[76:77], v72 offset:11520
	ds_read_b64 v[78:79], v73 offset:11520
	v_xor_b32_e32 v72, 40, v93
	v_lshl_add_u32 v72, v72, 1, v101
	v_xor_b32_e32 v73, 40, v94
	v_fmac_f32_e32 v75, v71, v70
	s_movk_i32 s0, 0x60
	v_xor_b32_e32 v70, 48, v91
	v_mfma_f32_16x16x32_bf16 v[16:19], v[86:89], v[64:67], v[16:19]
	v_lshl_add_u32 v73, v73, 1, v101
	ds_read_b64 v[86:87], v72 offset:11520
	ds_read_b64 v[88:89], v73 offset:11520
	v_pk_mul_f32 v[20:21], v[20:21], v[68:69] op_sel_hi:[1,0]
	v_mfma_f32_16x16x32_bf16 v[12:15], v[96:99], v[64:67], v[12:15]
	v_mul_f32_e64 v22, v22, v68
	v_mul_f32_e64 v23, v23, v68
	v_cndmask_b32_e64 v96, v69, v95, s[6:7]
	v_xad_u32 v69, v90, s0, v101
	v_lshl_add_u32 v72, v70, 1, v101
	ds_read_b64 v[70:71], v69 offset:13824
	ds_read_b64 v[72:73], v72 offset:13824
	v_pk_mul_f32 v[32:33], v[32:33], v[68:69] op_sel_hi:[1,0]
	v_pk_mul_f32 v[34:35], v[34:35], v[68:69] op_sel_hi:[1,0]
	v_xor_b32_e32 v69, 48, v93
	v_lshl_add_u32 v69, v69, 1, v101
	v_xor_b32_e32 v74, 48, v94
	s_waitcnt lgkmcnt(0)
	v_mfma_f32_16x16x32_bf16 v[32:35], v[70:73], v[60:63], v[32:35]
	s_movk_i32 s0, 0x70
	v_xor_b32_e32 v70, 56, v91
	v_lshl_add_u32 v74, v74, 1, v101
	v_mfma_f32_16x16x32_bf16 v[20:23], v[76:79], v[60:63], v[20:23]
	ds_read_b64 v[76:77], v69 offset:13824
	ds_read_b64 v[78:79], v74 offset:13824
	v_xad_u32 v69, v90, s0, v101
	v_lshl_add_u32 v72, v70, 1, v101
	ds_read_b64 v[70:71], v69 offset:16128
	ds_read_b64 v[72:73], v72 offset:16128
	v_xor_b32_e32 v69, 56, v93
	v_lshl_add_u32 v69, v69, 1, v101
	v_xor_b32_e32 v74, 56, v94
	v_mfma_f32_16x16x32_bf16 v[24:27], v[80:83], v[64:67], v[24:27]
	v_lshl_add_u32 v74, v74, 1, v101
	ds_read_b64 v[80:81], v69 offset:16128
	ds_read_b64 v[82:83], v74 offset:16128
	v_pk_mul_f32 v[28:29], v[28:29], v[68:69] op_sel_hi:[1,0]
	v_pk_mul_f32 v[30:31], v[30:31], v[68:69] op_sel_hi:[1,0]
	v_ashrrev_i32_e32 v97, 31, v96
	v_mfma_f32_16x16x32_bf16 v[20:23], v[86:89], v[64:67], v[20:23]
	v_lshl_add_u64 v[0:1], v[0:1], 0, v[96:97]
	v_lshlrev_b64 v[0:1], 12, v[0:1]
	v_lshl_add_u64 v[0:1], v[84:85], 0, v[0:1]
	s_waitcnt lgkmcnt(2)
	v_mfma_f32_16x16x32_bf16 v[28:31], v[70:73], v[60:63], v[28:31]
	global_store_dword v[0:1], v75, off
	v_mfma_f32_16x16x32_bf16 v[32:35], v[76:79], v[64:67], v[32:35]
	s_waitcnt lgkmcnt(0)
	v_mfma_f32_16x16x32_bf16 v[28:31], v[80:83], v[64:67], v[28:31]
	s_and_saveexec_b64 s[0:1], vcc
	s_cbranch_execz .LBB0_644
	v_and_b32_e32 v0, 7, v3
	v_ashrrev_i32_e32 v1, 3, v3
	v_cmp_eq_u32_e32 vcc, 0, v0
	s_and_saveexec_b64 s[12:13], vcc
	s_cbranch_execz .LBB0_643
	s_and_b64 s[66:67], s[14:15], exec
	s_cselect_b32 s66, s55, s64
	s_add_i32 s67, 16, 0x1c900
	s_add_i32 vcc_lo, 16, 0x25900
	s_and_b64 s[64:65], s[14:15], exec
	s_cselect_b32 s64, vcc_lo, s67
	v_lshlrev_b32_e32 v3, 2, v1
	v_add_u32_e32 v60, s64, v3
	v_add_u32_e32 v3, s66, v3
	s_waitcnt vmcnt(17)
	ds_write_b32 v3, v122
	ds_write_b32 v60, v110
	s_branch .LBB0_643
